# v_k9 + attn_scan: the 128 scan items pinned to blocks 0..127 (one scan per CU, never two on one CU); everything else via the dynamic queue
# speedup vs baseline: 1.0309x; 1.0080x over previous
; DI void phase_attn_scan(const Params& p, int l, int half, char* smem, int rep) {
;   __shared__ int s_item;
;   const int n_scan = 128, n_lat = 3 * 512, n_ctx = (l == 0) ? 96 : 0;
;   const int n_gate = ((l == 0) ? 68 : 64) * 32;
;   const int n_conv = (l == 0 && half == 0) ? 128 : 0;
;   const int total = n_scan + n_conv + n_lat + n_ctx + n_gate;
;   unsigned* cnt = p.cnt + (l * 2 + half) + 8 * rep;
;   for (;;) {
;     __syncthreads();
;     if (threadIdx.x == 0) s_item = (int)atomicAdd(cnt, 1u);
;     __syncthreads();
;     int it = s_item;
;     if (it >= total) break;
.LBB0_151:
	s_and_b64 vcc, exec, s[0:1]
	s_cbranch_vccz .LBB0_941
	v_readlane_b32 s0, v255, 20
	s_cmp_gt_i32 s0, 0
	s_mov_b64 s[0:1], -1
	s_cbranch_scc0 .LBB0_939
	v_readlane_b32 s0, v255, 20
	s_cmp_gt_i32 s0, 1
	s_mov_b64 s[0:1], -1
	s_cbranch_scc0 .LBB0_408
	v_readlane_b32 s0, v252, 2
	s_add_i32 s0, s0, 11
	s_cmp_gt_u32 s0, 26
	s_cselect_b64 s[12:13], -1, 0
	v_writelane_b32 v255, s12, 25
	v_readlane_b32 s1, v252, 3
	s_mov_b64 s[86:87], s[66:67]
	v_writelane_b32 v255, s13, 26
	s_mov_b64 s[84:85], s[64:65]
	v_readlane_b32 s12, v255, 17
	v_readlane_b32 s26, v255, 19
	s_or_b32 s1, s26, s12
	s_cmp_eq_u32 s1, 0
	s_mov_b64 s[82:83], s[62:63]
	s_mov_b64 s[80:81], s[60:61]
	s_mov_b64 s[78:79], s[58:59]
	s_mov_b64 s[76:77], s[56:57]
	s_mov_b64 s[74:75], s[54:55]
	s_mov_b64 s[72:73], s[52:53]
	s_mov_b32 s60, s12
	s_cselect_b32 s12, 0x80, 0
	s_cmp_lt_u32 s0, 27
	s_movk_i32 s0, 0x880
	s_cselect_b32 s21, s0, 0x800
	s_movk_i32 s0, 0xf0a0
	s_cselect_b32 s0, s0, 0xfffff180
	v_readlane_b32 s13, v255, 18
	v_writelane_b32 v255, s0, 30
	s_movk_i32 s0, 0xf920
	s_cselect_b32 s13, 0x60, 0
	s_cselect_b32 s0, s0, 0xfffff980
	v_writelane_b32 v255, s0, 27
	s_or_b32 s0, s21, s13
	s_add_i32 s0, s0, s12
	s_add_i32 s69, s0, 0x680
	s_lshl_b32 s0, s60, 1
	s_add_i32 s0, s0, s26
	s_ashr_i32 s1, s0, 31
	s_lshl_b64 s[0:1], s[0:1], 2
	s_add_u32 s0, s74, s0
	s_addc_u32 s1, s75, s1
	v_writelane_b32 v255, s0, 23
	s_lshl_b32 s28, s12, 8
	s_ashr_i32 s61, s60, 31
	v_writelane_b32 v255, s1, 24
	s_or_b32 s0, s13, 0x600
	v_writelane_b32 v255, s0, 32
	s_or_b32 s0, s0, s21
	v_writelane_b32 v255, s0, 28
	s_mul_i32 s0, s26, 0x4400
	v_writelane_b32 v255, s0, 34
	s_ashr_i32 s0, s0, 31
	s_mul_i32 s1, s60, 0x1f00
	v_writelane_b32 v255, s0, 35
	s_mul_hi_i32 s0, s60, 0x1f00
	s_add_u32 s1, s1, 0xf00
	v_writelane_b32 v255, s1, 36
	s_addc_u32 s0, s0, 0
	v_writelane_b32 v255, s0, 37
	s_lshl_b32 s0, s60, 12
	s_ashr_i32 s1, s0, 31
	s_lshl_b32 s12, s60, 6
	v_readlane_b32 s36, v252, 38
	s_ashr_i32 s13, s12, 31
	s_lshl_b64 s[0:1], s[0:1], 2
	v_readlane_b32 s38, v252, 40
	v_readlane_b32 s39, v252, 41
	s_add_u32 s0, s38, s0
	v_writelane_b32 v255, s0, 38
	s_addc_u32 s0, s39, s1
	v_writelane_b32 v255, s0, 39
	s_mov_b32 s0, s60
	v_writelane_b32 v255, s0, 17
	v_readlane_b32 s37, v252, 39
	s_mov_b32 s29, s27
	v_writelane_b32 v255, s1, 18
	s_lshl_b64 s[0:1], s[60:61], 2
	s_mov_b64 s[52:53], s[72:73]
	s_add_u32 s0, s52, s0
	s_addc_u32 s1, s53, s1
	v_writelane_b32 v255, s0, 40
	s_mov_b64 s[54:55], s[74:75]
	s_mov_b64 s[56:57], s[76:77]
	v_writelane_b32 v255, s1, 41
	s_lshl_b64 s[0:1], s[12:13], 2
	s_add_u32 s0, s36, s0
	s_addc_u32 s1, s37, s1
	v_writelane_b32 v255, s0, 42
	s_mov_b64 s[58:59], s[78:79]
	s_mov_b64 s[60:61], s[80:81]
	s_mov_b64 s[62:63], s[82:83]
	s_mov_b64 s[64:65], s[84:85]
	s_mov_b64 s[66:67], s[86:87]
	v_writelane_b32 v255, s1, 43
	v_readlane_b32 s40, v252, 42
	v_readlane_b32 s41, v252, 43
	v_readlane_b32 s42, v252, 44
	v_readlane_b32 s43, v252, 45
	v_readlane_b32 s44, v252, 46
	v_readlane_b32 s45, v252, 47
	v_readlane_b32 s46, v252, 48
	v_readlane_b32 s47, v252, 49
	v_readlane_b32 s48, v252, 50
	v_readlane_b32 s49, v252, 51
	v_readlane_b32 s50, v252, 52
	v_readlane_b32 s51, v252, 53
	s_add_i32 s1, s2, 1
	s_cmp_lt_u32 s2, 128
	s_cselect_b32 s1, s1, 0
	s_nop 0
	v_writelane_b32 v255, s1, 59
	s_branch .LBB0_158

; DI void phase_attn_scan(const Params& p, int l, int half, char* smem, int rep) {
;     ...
;   for (;;) {
;     __syncthreads();
;     if (threadIdx.x == 0) s_item = (int)atomicAdd(cnt, 1u);
;     __syncthreads();
;     int it = s_item;
;     if (it >= total) break;
.LBB0_158:
	s_barrier
	s_mov_b64 s[0:1], exec
	v_readlane_b32 s12, v252, 0
	v_readlane_b32 s13, v252, 1
	s_and_b64 s[12:13], s[0:1], s[12:13]
	s_mov_b64 exec, s[12:13]
	s_cbranch_execz .LBB0_162
	v_readlane_b32 s12, v255, 59
	s_cmp_eq_u32 s12, 0
	s_cbranch_scc1 .Lq_fetch
	s_add_i32 s12, s12, -1
	s_waitcnt vmcnt(3)
	v_mov_b32_e32 v0, s12
	v_writelane_b32 v255, 0, 59
	ds_write_b32 v200, v0
	s_branch .LBB0_162

; DI void phase_attn_scan(const Params& p, int l, int half, char* smem, int rep) {
;     ...
;   for (;;) {
;     __syncthreads();
;     if (threadIdx.x == 0) s_item = (int)atomicAdd(cnt, 1u);
;     __syncthreads();
;     int it = s_item;
;     if (it >= total) break;
.LBB0_161:
	s_or_b64 exec, exec, s[12:13]
	s_waitcnt vmcnt(0)
	v_readfirstlane_b32 s12, v1
	s_nop 1
	v_add_u32_e32 v0, s12, v0
	v_add_u32_e32 v0, 0x80, v0
	ds_write_b32 v200, v0
